# P11: nt cache policy on the write-once h stores of the gate/up GEMM epilogue
# speedup vs baseline: 1.0048x; 1.0048x over previous
.LBB0_1307:
	v_mov_b32_e32 v150, v124
	v_mov_b32_e32 v151, v116
	s_waitcnt vmcnt(0)
	v_pk_mul_f32 v[150:151], v[150:151], v[128:129] op_sel_hi:[1,0]
	v_mov_b32_e32 v152, v120
	v_mul_f32_e32 v116, 0xbfb8aa3b, v151
	v_exp_f32_e32 v116, v116
	v_mov_b32_e32 v153, v112
	v_pk_mul_f32 v[152:153], v[152:153], v[128:129] op_sel_hi:[1,0]
	s_lshl_b32 s20, s20, 7
	v_mul_f32_e32 v112, 0xbfb8aa3b, v153
	v_exp_f32_e32 v112, v112
	v_add_f32_e32 v116, 1.0, v116
	v_rcp_f32_e32 v116, v116
	s_ashr_i32 s21, s20, 31
	v_add_f32_e32 v112, 1.0, v112
	v_rcp_f32_e32 v112, v112
	v_mul_f32_e32 v116, v151, v116
	v_mul_f32_e32 v124, v150, v116
	v_mov_b32_e32 v116, v125
	v_pk_mul_f32 v[116:117], v[116:117], v[128:129] op_sel_hi:[1,0]
	v_mul_f32_e32 v120, v153, v112
	v_mul_f32_e32 v112, 0xbfb8aa3b, v117
	v_exp_f32_e32 v125, v112
	v_mov_b32_e32 v112, v121
	v_pk_mul_f32 v[112:113], v[112:113], v[128:129] op_sel_hi:[1,0]
	v_mul_f32_e32 v150, v152, v120
	v_mul_f32_e32 v121, 0xbfb8aa3b, v113
	v_exp_f32_e32 v121, v121
	v_add_f32_e32 v120, 1.0, v125
	v_rcp_f32_e32 v125, v120
	s_lshl_b64 s[20:21], s[20:21], 1
	v_add_f32_e32 v120, 1.0, v121
	v_rcp_f32_e32 v151, v120
	v_mov_b32_e32 v120, v126
	v_mov_b32_e32 v121, v118
	v_pk_mul_f32 v[120:121], v[120:121], v[128:129] op_sel_hi:[1,0]
	v_mul_f32_e32 v117, v117, v125
	v_mul_f32_e32 v118, 0xbfb8aa3b, v121
	v_exp_f32_e32 v118, v118
	v_mul_f32_e32 v125, v116, v117
	v_mov_b32_e32 v117, v114
	v_mul_f32_e32 v113, v113, v151
	v_add_f32_e32 v116, 1.0, v118
	v_rcp_f32_e32 v118, v116
	v_mov_b32_e32 v116, v122
	v_pk_mul_f32 v[116:117], v[116:117], v[128:129] op_sel_hi:[1,0]
	v_mul_f32_e32 v122, v112, v113
	v_mul_f32_e32 v114, 0xbfb8aa3b, v117
	v_exp_f32_e32 v114, v114
	v_mul_f32_e32 v112, v121, v118
	v_mul_f32_e32 v120, v120, v112
	v_mov_b32_e32 v118, v127
	v_add_f32_e32 v112, 1.0, v114
	v_rcp_f32_e32 v121, v112
	v_pk_mul_f32 v[112:113], v[118:119], v[128:129] op_sel_hi:[1,0]
	v_or_b32_e32 v145, 16, v148
	v_mul_f32_e32 v114, 0xbfb8aa3b, v113
	v_exp_f32_e32 v118, v114
	v_mov_b32_e32 v114, v123
	v_pk_mul_f32 v[114:115], v[114:115], v[128:129] op_sel_hi:[1,0]
	v_mul_f32_e32 v117, v117, v121
	v_mul_f32_e32 v119, 0xbfb8aa3b, v115
	v_exp_f32_e32 v119, v119
	v_add_f32_e32 v118, 1.0, v118
	v_rcp_f32_e32 v118, v118
	v_mul_f32_e32 v121, v116, v117
	v_add_f32_e32 v119, 1.0, v119
	v_rcp_f32_e32 v119, v119
	v_mul_f32_e32 v113, v113, v118
	v_mul_f32_e32 v112, v112, v113
	v_cvt_pk_bf16_f32 v117, v120, v112
	v_mul_f32_e32 v113, v115, v119
	v_mul_f32_e32 v113, v114, v113
	v_cvt_pk_bf16_f32 v119, v121, v113
	v_mov_b64_e32 v[112:113], s[66:67]
	v_mad_i64_i32 v[114:115], s[22:23], v148, s36, v[112:113]
	v_lshl_add_u64 v[114:115], v[114:115], 0, s[20:21]
	v_and_b32_e32 v128, 0xc0, v143
	v_lshl_add_u64 v[120:121], v[114:115], 0, v[128:129]
	v_and_b32_e32 v114, 48, v143
	v_mov_b32_e32 v115, v129
	v_lshl_add_u64 v[120:121], v[120:121], 0, v[114:115]
	v_or_b32_e32 v147, 32, v148
	v_or_b32_e32 v149, 48, v148
	v_add_u32_e32 v141, 0x80, v148
	v_add_u32_e32 v139, 0x90, v148
	v_add_u32_e32 v135, 0xa0, v148
	v_add_u32_e32 v131, 0xb0, v148
	v_cvt_pk_bf16_f32 v116, v124, v125
	v_cvt_pk_bf16_f32 v118, v150, v122
	global_store_dwordx4 v[120:121], v[116:119], off nt
	s_nop 1
	v_mov_b32_e32 v116, v108
	v_mov_b32_e32 v117, v100
	v_pk_mul_f32 v[116:117], v[116:117], v[146:147] op_sel_hi:[1,0]
	v_mov_b32_e32 v118, v104
	v_mul_f32_e32 v100, 0xbfb8aa3b, v117
	v_exp_f32_e32 v100, v100
	v_mov_b32_e32 v119, v96
	v_pk_mul_f32 v[118:119], v[118:119], v[146:147] op_sel_hi:[1,0]
	v_add_f32_e32 v100, 1.0, v100
	v_mul_f32_e32 v96, 0xbfb8aa3b, v119
	v_exp_f32_e32 v96, v96
	v_rcp_f32_e32 v100, v100
	v_add_f32_e32 v96, 1.0, v96
	v_rcp_f32_e32 v96, v96
	v_mul_f32_e32 v100, v117, v100
	v_mul_f32_e32 v108, v116, v100
	v_mov_b32_e32 v100, v109
	v_pk_mul_f32 v[100:101], v[100:101], v[146:147] op_sel_hi:[1,0]
	v_mul_f32_e32 v104, v119, v96
	v_mul_f32_e32 v96, 0xbfb8aa3b, v101
	v_exp_f32_e32 v109, v96
	v_mov_b32_e32 v96, v105
	v_pk_mul_f32 v[96:97], v[96:97], v[146:147] op_sel_hi:[1,0]
	v_mul_f32_e32 v116, v118, v104
	v_mul_f32_e32 v105, 0xbfb8aa3b, v97
	v_exp_f32_e32 v105, v105
	v_add_f32_e32 v104, 1.0, v109
	v_rcp_f32_e32 v109, v104
	v_add_f32_e32 v104, 1.0, v105
	v_rcp_f32_e32 v117, v104
	v_mov_b32_e32 v104, v110
	v_mov_b32_e32 v105, v102
	v_pk_mul_f32 v[104:105], v[104:105], v[146:147] op_sel_hi:[1,0]
	v_mul_f32_e32 v101, v101, v109
	v_mul_f32_e32 v102, 0xbfb8aa3b, v105
	v_exp_f32_e32 v102, v102
	v_mul_f32_e32 v109, v100, v101
	v_mov_b32_e32 v101, v98
	v_mul_f32_e32 v97, v97, v117
	v_add_f32_e32 v100, 1.0, v102
	v_rcp_f32_e32 v102, v100
	v_mov_b32_e32 v100, v106
	v_pk_mul_f32 v[100:101], v[100:101], v[146:147] op_sel_hi:[1,0]
	v_mul_f32_e32 v106, v96, v97
	v_mul_f32_e32 v98, 0xbfb8aa3b, v101
	v_exp_f32_e32 v98, v98
	v_mul_f32_e32 v96, v105, v102
	v_mul_f32_e32 v104, v104, v96
	v_mov_b32_e32 v102, v111
	v_add_f32_e32 v96, 1.0, v98
	v_rcp_f32_e32 v105, v96
	v_pk_mul_f32 v[96:97], v[102:103], v[146:147] op_sel_hi:[1,0]
	v_mul_f32_e32 v101, v101, v105
	v_mul_f32_e32 v98, 0xbfb8aa3b, v97
	v_exp_f32_e32 v102, v98
	v_mov_b32_e32 v98, v107
	v_pk_mul_f32 v[98:99], v[98:99], v[146:147] op_sel_hi:[1,0]
	v_mul_f32_e32 v100, v100, v101
	v_mul_f32_e32 v103, 0xbfb8aa3b, v99
	v_exp_f32_e32 v103, v103
	v_add_f32_e32 v102, 1.0, v102
	v_rcp_f32_e32 v102, v102
	v_add_f32_e32 v103, 1.0, v103
	v_rcp_f32_e32 v103, v103
	v_mul_f32_e32 v97, v97, v102
	v_mul_f32_e32 v97, v96, v97
	v_cvt_pk_bf16_f32 v97, v104, v97
	v_mul_f32_e32 v96, v99, v103
	v_mul_f32_e32 v99, v98, v96
	v_cvt_pk_bf16_f32 v99, v100, v99
	v_mad_i64_i32 v[100:101], s[22:23], v145, s36, v[112:113]
	v_lshl_add_u64 v[100:101], v[100:101], 0, s[20:21]
	v_lshl_add_u64 v[100:101], v[100:101], 0, v[128:129]
	v_lshl_add_u64 v[100:101], v[100:101], 0, v[114:115]
	v_cvt_pk_bf16_f32 v96, v108, v109
	v_cvt_pk_bf16_f32 v98, v116, v106
	global_store_dwordx4 v[100:101], v[96:99], off nt
	s_nop 1
	v_mov_b32_e32 v96, v92
	v_mov_b32_e32 v97, v84
	v_pk_mul_f32 v[96:97], v[96:97], v[144:145] op_sel_hi:[1,0]
	v_mov_b32_e32 v98, v88
	v_mul_f32_e32 v84, 0xbfb8aa3b, v97
	v_exp_f32_e32 v84, v84
	v_mov_b32_e32 v99, v80
	v_pk_mul_f32 v[98:99], v[98:99], v[144:145] op_sel_hi:[1,0]
	v_add_f32_e32 v84, 1.0, v84
	v_mul_f32_e32 v80, 0xbfb8aa3b, v99
	v_exp_f32_e32 v80, v80
	v_rcp_f32_e32 v84, v84
	v_add_f32_e32 v80, 1.0, v80
	v_rcp_f32_e32 v80, v80
	v_mul_f32_e32 v84, v97, v84
	v_mul_f32_e32 v92, v96, v84
	v_mov_b32_e32 v84, v93
	v_pk_mul_f32 v[84:85], v[84:85], v[144:145] op_sel_hi:[1,0]
	v_mul_f32_e32 v88, v99, v80
	v_mul_f32_e32 v80, 0xbfb8aa3b, v85
	v_exp_f32_e32 v93, v80
	v_mov_b32_e32 v80, v89
	v_pk_mul_f32 v[80:81], v[80:81], v[144:145] op_sel_hi:[1,0]
	v_mul_f32_e32 v96, v98, v88
	v_mul_f32_e32 v89, 0xbfb8aa3b, v81
	v_exp_f32_e32 v89, v89
	v_add_f32_e32 v88, 1.0, v93
	v_rcp_f32_e32 v93, v88
	v_add_f32_e32 v88, 1.0, v89
	v_rcp_f32_e32 v97, v88
	v_mov_b32_e32 v88, v94
	v_mov_b32_e32 v89, v86
	v_pk_mul_f32 v[88:89], v[88:89], v[144:145] op_sel_hi:[1,0]
	v_mul_f32_e32 v85, v85, v93
	v_mul_f32_e32 v86, 0xbfb8aa3b, v89
	v_exp_f32_e32 v86, v86
	v_mul_f32_e32 v93, v84, v85
	v_mov_b32_e32 v85, v82
	v_mul_f32_e32 v81, v81, v97
	v_add_f32_e32 v84, 1.0, v86
	v_rcp_f32_e32 v86, v84
	v_mov_b32_e32 v84, v90
	v_pk_mul_f32 v[84:85], v[84:85], v[144:145] op_sel_hi:[1,0]
	v_mul_f32_e32 v90, v80, v81
	v_mul_f32_e32 v82, 0xbfb8aa3b, v85
	v_exp_f32_e32 v82, v82
	v_mul_f32_e32 v80, v89, v86
	v_mul_f32_e32 v88, v88, v80
	v_mov_b32_e32 v86, v95
	v_add_f32_e32 v80, 1.0, v82
	v_rcp_f32_e32 v89, v80
	v_pk_mul_f32 v[80:81], v[86:87], v[144:145] op_sel_hi:[1,0]
	v_mul_f32_e32 v85, v85, v89
	v_mul_f32_e32 v82, 0xbfb8aa3b, v81
	v_exp_f32_e32 v86, v82
	v_mov_b32_e32 v82, v91
	v_pk_mul_f32 v[82:83], v[82:83], v[144:145] op_sel_hi:[1,0]
	v_mul_f32_e32 v84, v84, v85
	v_mul_f32_e32 v87, 0xbfb8aa3b, v83
	v_exp_f32_e32 v87, v87
	v_add_f32_e32 v86, 1.0, v86
	v_rcp_f32_e32 v86, v86
	v_add_f32_e32 v87, 1.0, v87
	v_rcp_f32_e32 v87, v87
	v_mul_f32_e32 v81, v81, v86
	v_mul_f32_e32 v81, v80, v81
	v_cvt_pk_bf16_f32 v81, v88, v81
	v_mul_f32_e32 v80, v83, v87
	v_mul_f32_e32 v83, v82, v80
	v_cvt_pk_bf16_f32 v83, v84, v83
	v_mad_i64_i32 v[84:85], s[22:23], v147, s36, v[112:113]
	v_lshl_add_u64 v[84:85], v[84:85], 0, s[20:21]
	v_lshl_add_u64 v[84:85], v[84:85], 0, v[128:129]
	v_lshl_add_u64 v[84:85], v[84:85], 0, v[114:115]
	v_cvt_pk_bf16_f32 v80, v92, v93
	v_cvt_pk_bf16_f32 v82, v96, v90
	global_store_dwordx4 v[84:85], v[80:83], off nt
	s_nop 1
	v_mov_b32_e32 v80, v76
	v_mov_b32_e32 v81, v68
	v_pk_mul_f32 v[80:81], v[80:81], v[142:143] op_sel_hi:[1,0]
	v_mov_b32_e32 v82, v72
	v_mul_f32_e32 v68, 0xbfb8aa3b, v81
	v_exp_f32_e32 v68, v68
	v_mov_b32_e32 v83, v64
	v_pk_mul_f32 v[82:83], v[82:83], v[142:143] op_sel_hi:[1,0]
	v_add_f32_e32 v68, 1.0, v68
	v_mul_f32_e32 v64, 0xbfb8aa3b, v83
	v_exp_f32_e32 v64, v64
	v_rcp_f32_e32 v68, v68
	v_add_f32_e32 v64, 1.0, v64
	v_rcp_f32_e32 v64, v64
	v_mul_f32_e32 v68, v81, v68
	v_mul_f32_e32 v76, v80, v68
	v_mov_b32_e32 v68, v77
	v_pk_mul_f32 v[68:69], v[68:69], v[142:143] op_sel_hi:[1,0]
	v_mul_f32_e32 v72, v83, v64
	v_mul_f32_e32 v64, 0xbfb8aa3b, v69
	v_exp_f32_e32 v77, v64
	v_mov_b32_e32 v64, v73
	v_pk_mul_f32 v[64:65], v[64:65], v[142:143] op_sel_hi:[1,0]
	v_mul_f32_e32 v80, v82, v72
	v_mul_f32_e32 v73, 0xbfb8aa3b, v65
	v_exp_f32_e32 v73, v73
	v_add_f32_e32 v72, 1.0, v77
	v_rcp_f32_e32 v77, v72
	v_add_f32_e32 v72, 1.0, v73
	v_rcp_f32_e32 v81, v72
	v_mov_b32_e32 v72, v78
	v_mov_b32_e32 v73, v70
	v_pk_mul_f32 v[72:73], v[72:73], v[142:143] op_sel_hi:[1,0]
	v_mul_f32_e32 v69, v69, v77
	v_mul_f32_e32 v70, 0xbfb8aa3b, v73
	v_exp_f32_e32 v70, v70
	v_mul_f32_e32 v77, v68, v69
	v_mov_b32_e32 v69, v66
	v_mul_f32_e32 v65, v65, v81
	v_add_f32_e32 v68, 1.0, v70
	v_rcp_f32_e32 v70, v68
	v_mov_b32_e32 v68, v74
	v_pk_mul_f32 v[68:69], v[68:69], v[142:143] op_sel_hi:[1,0]
	v_mul_f32_e32 v74, v64, v65
	v_mul_f32_e32 v66, 0xbfb8aa3b, v69
	v_exp_f32_e32 v66, v66
	v_mul_f32_e32 v64, v73, v70
	v_mul_f32_e32 v72, v72, v64
	v_mov_b32_e32 v70, v79
	v_add_f32_e32 v64, 1.0, v66
	v_rcp_f32_e32 v73, v64
	v_pk_mul_f32 v[64:65], v[70:71], v[142:143] op_sel_hi:[1,0]
	v_mul_f32_e32 v69, v69, v73
	v_mul_f32_e32 v66, 0xbfb8aa3b, v65
	v_exp_f32_e32 v70, v66
	v_mov_b32_e32 v66, v75
	v_pk_mul_f32 v[66:67], v[66:67], v[142:143] op_sel_hi:[1,0]
	v_mul_f32_e32 v68, v68, v69
	v_mul_f32_e32 v71, 0xbfb8aa3b, v67
	v_exp_f32_e32 v71, v71
	v_add_f32_e32 v70, 1.0, v70
	v_rcp_f32_e32 v70, v70
	v_add_f32_e32 v71, 1.0, v71
	v_rcp_f32_e32 v71, v71
	v_mul_f32_e32 v65, v65, v70
	v_mul_f32_e32 v65, v64, v65
	v_cvt_pk_bf16_f32 v65, v72, v65
	v_mul_f32_e32 v64, v67, v71
	v_mul_f32_e32 v67, v66, v64
	v_cvt_pk_bf16_f32 v67, v68, v67
	v_mad_i64_i32 v[68:69], s[22:23], v149, s36, v[112:113]
	v_lshl_add_u64 v[68:69], v[68:69], 0, s[20:21]
	v_lshl_add_u64 v[68:69], v[68:69], 0, v[128:129]
	v_lshl_add_u64 v[68:69], v[68:69], 0, v[114:115]
	v_cvt_pk_bf16_f32 v64, v76, v77
	v_cvt_pk_bf16_f32 v66, v80, v74
	global_store_dwordx4 v[68:69], v[64:67], off nt
	s_nop 1
	v_mov_b32_e32 v64, v60
	v_mov_b32_e32 v65, v52
	v_pk_mul_f32 v[64:65], v[64:65], v[140:141] op_sel_hi:[1,0]
	v_mov_b32_e32 v66, v56
	v_mul_f32_e32 v52, 0xbfb8aa3b, v65
	v_exp_f32_e32 v52, v52
	v_mov_b32_e32 v67, v48
	v_pk_mul_f32 v[66:67], v[66:67], v[140:141] op_sel_hi:[1,0]
	v_add_f32_e32 v52, 1.0, v52
	v_mul_f32_e32 v48, 0xbfb8aa3b, v67
	v_exp_f32_e32 v48, v48
	v_rcp_f32_e32 v52, v52
	v_add_f32_e32 v48, 1.0, v48
	v_rcp_f32_e32 v48, v48
	v_mul_f32_e32 v52, v65, v52
	v_mul_f32_e32 v60, v64, v52
	v_mov_b32_e32 v52, v61
	v_pk_mul_f32 v[52:53], v[52:53], v[140:141] op_sel_hi:[1,0]
	v_mul_f32_e32 v56, v67, v48
	v_mul_f32_e32 v48, 0xbfb8aa3b, v53
	v_exp_f32_e32 v61, v48
	v_mov_b32_e32 v48, v57
	v_pk_mul_f32 v[48:49], v[48:49], v[140:141] op_sel_hi:[1,0]
	v_mul_f32_e32 v64, v66, v56
	v_mul_f32_e32 v57, 0xbfb8aa3b, v49
	v_exp_f32_e32 v57, v57
	v_add_f32_e32 v56, 1.0, v61
	v_rcp_f32_e32 v61, v56
	v_add_f32_e32 v56, 1.0, v57
	v_rcp_f32_e32 v65, v56
	v_mov_b32_e32 v56, v62
	v_mov_b32_e32 v57, v54
	v_pk_mul_f32 v[56:57], v[56:57], v[140:141] op_sel_hi:[1,0]
	v_mul_f32_e32 v53, v53, v61
	v_mul_f32_e32 v54, 0xbfb8aa3b, v57
	v_exp_f32_e32 v54, v54
	v_mul_f32_e32 v61, v52, v53
	v_mov_b32_e32 v53, v50
	v_mul_f32_e32 v49, v49, v65
	v_add_f32_e32 v52, 1.0, v54
	v_rcp_f32_e32 v54, v52
	v_mov_b32_e32 v52, v58
	v_pk_mul_f32 v[52:53], v[52:53], v[140:141] op_sel_hi:[1,0]
	v_mul_f32_e32 v58, v48, v49
	v_mul_f32_e32 v50, 0xbfb8aa3b, v53
	v_exp_f32_e32 v50, v50
	v_mul_f32_e32 v48, v57, v54
	v_mul_f32_e32 v56, v56, v48
	v_mov_b32_e32 v54, v63
	v_add_f32_e32 v48, 1.0, v50
	v_rcp_f32_e32 v57, v48
	v_pk_mul_f32 v[48:49], v[54:55], v[140:141] op_sel_hi:[1,0]
	v_mul_f32_e32 v53, v53, v57
	v_mul_f32_e32 v50, 0xbfb8aa3b, v49
	v_exp_f32_e32 v54, v50
	v_mov_b32_e32 v50, v59
	v_pk_mul_f32 v[50:51], v[50:51], v[140:141] op_sel_hi:[1,0]
	v_mul_f32_e32 v52, v52, v53
	v_mul_f32_e32 v55, 0xbfb8aa3b, v51
	v_exp_f32_e32 v55, v55
	v_add_f32_e32 v54, 1.0, v54
	v_rcp_f32_e32 v54, v54
	v_add_f32_e32 v55, 1.0, v55
	v_rcp_f32_e32 v55, v55
	v_mul_f32_e32 v49, v49, v54
	v_mul_f32_e32 v49, v48, v49
	v_cvt_pk_bf16_f32 v49, v56, v49
	v_mul_f32_e32 v48, v51, v55
	v_mul_f32_e32 v51, v50, v48
	v_cvt_pk_bf16_f32 v51, v52, v51
	v_mad_i64_i32 v[52:53], s[22:23], v141, s36, v[112:113]
	v_lshl_add_u64 v[52:53], v[52:53], 0, s[20:21]
	v_lshl_add_u64 v[52:53], v[52:53], 0, v[128:129]
	v_lshl_add_u64 v[52:53], v[52:53], 0, v[114:115]
	v_cvt_pk_bf16_f32 v48, v60, v61
	v_cvt_pk_bf16_f32 v50, v64, v58
	global_store_dwordx4 v[52:53], v[48:51], off nt
	s_nop 1
	v_mov_b32_e32 v48, v44
	v_mov_b32_e32 v49, v36
	v_pk_mul_f32 v[48:49], v[48:49], v[138:139] op_sel_hi:[1,0]
	v_mov_b32_e32 v50, v40
	v_mul_f32_e32 v36, 0xbfb8aa3b, v49
	v_exp_f32_e32 v36, v36
	v_mov_b32_e32 v51, v32
	v_pk_mul_f32 v[50:51], v[50:51], v[138:139] op_sel_hi:[1,0]
	v_add_f32_e32 v36, 1.0, v36
	v_mul_f32_e32 v32, 0xbfb8aa3b, v51
	v_exp_f32_e32 v32, v32
	v_rcp_f32_e32 v36, v36
	v_add_f32_e32 v32, 1.0, v32
	v_rcp_f32_e32 v32, v32
	v_mul_f32_e32 v36, v49, v36
	v_mul_f32_e32 v44, v48, v36
	v_mov_b32_e32 v36, v45
	v_pk_mul_f32 v[36:37], v[36:37], v[138:139] op_sel_hi:[1,0]
	v_mul_f32_e32 v40, v51, v32
	v_mul_f32_e32 v32, 0xbfb8aa3b, v37
	v_exp_f32_e32 v45, v32
	v_mov_b32_e32 v32, v41
	v_pk_mul_f32 v[32:33], v[32:33], v[138:139] op_sel_hi:[1,0]
	v_mul_f32_e32 v48, v50, v40
	v_mul_f32_e32 v41, 0xbfb8aa3b, v33
	v_exp_f32_e32 v41, v41
	v_add_f32_e32 v40, 1.0, v45
	v_rcp_f32_e32 v45, v40
	v_add_f32_e32 v40, 1.0, v41
	v_rcp_f32_e32 v49, v40
	v_mov_b32_e32 v40, v46
	v_mov_b32_e32 v41, v38
	v_pk_mul_f32 v[40:41], v[40:41], v[138:139] op_sel_hi:[1,0]
	v_mul_f32_e32 v37, v37, v45
	v_mul_f32_e32 v38, 0xbfb8aa3b, v41
	v_exp_f32_e32 v38, v38
	v_mul_f32_e32 v45, v36, v37
	v_mov_b32_e32 v37, v34
	v_mul_f32_e32 v33, v33, v49
	v_add_f32_e32 v36, 1.0, v38
	v_rcp_f32_e32 v38, v36
	v_mov_b32_e32 v36, v42
	v_pk_mul_f32 v[36:37], v[36:37], v[138:139] op_sel_hi:[1,0]
	v_mul_f32_e32 v42, v32, v33
	v_mul_f32_e32 v34, 0xbfb8aa3b, v37
	v_exp_f32_e32 v34, v34
	v_mul_f32_e32 v32, v41, v38
	v_mul_f32_e32 v40, v40, v32
	v_mov_b32_e32 v38, v47
	v_add_f32_e32 v32, 1.0, v34
	v_rcp_f32_e32 v41, v32
	v_pk_mul_f32 v[32:33], v[38:39], v[138:139] op_sel_hi:[1,0]
	v_mul_f32_e32 v37, v37, v41
	v_mul_f32_e32 v34, 0xbfb8aa3b, v33
	v_exp_f32_e32 v38, v34
	v_mov_b32_e32 v34, v43
	v_pk_mul_f32 v[34:35], v[34:35], v[138:139] op_sel_hi:[1,0]
	v_mul_f32_e32 v36, v36, v37
	v_mul_f32_e32 v39, 0xbfb8aa3b, v35
	v_exp_f32_e32 v39, v39
	v_add_f32_e32 v38, 1.0, v38
	v_rcp_f32_e32 v38, v38
	v_add_f32_e32 v39, 1.0, v39
	v_rcp_f32_e32 v39, v39
	v_mul_f32_e32 v33, v33, v38
	v_mul_f32_e32 v33, v32, v33
	v_cvt_pk_bf16_f32 v33, v40, v33
	v_mul_f32_e32 v32, v35, v39
	v_mul_f32_e32 v35, v34, v32
	v_cvt_pk_bf16_f32 v35, v36, v35
	v_mad_i64_i32 v[36:37], s[22:23], v139, s36, v[112:113]
	v_lshl_add_u64 v[36:37], v[36:37], 0, s[20:21]
	v_lshl_add_u64 v[36:37], v[36:37], 0, v[128:129]
	v_lshl_add_u64 v[36:37], v[36:37], 0, v[114:115]
	v_cvt_pk_bf16_f32 v32, v44, v45
	v_cvt_pk_bf16_f32 v34, v48, v42
	global_store_dwordx4 v[36:37], v[32:35], off nt
	s_nop 1
	v_mov_b32_e32 v32, v28
	v_mov_b32_e32 v33, v20
	v_pk_mul_f32 v[32:33], v[32:33], v[134:135] op_sel_hi:[1,0]
	v_mov_b32_e32 v34, v24
	v_mul_f32_e32 v20, 0xbfb8aa3b, v33
	v_exp_f32_e32 v20, v20
	v_mov_b32_e32 v35, v16
	v_pk_mul_f32 v[34:35], v[34:35], v[134:135] op_sel_hi:[1,0]
	v_add_f32_e32 v20, 1.0, v20
	v_mul_f32_e32 v16, 0xbfb8aa3b, v35
	v_exp_f32_e32 v16, v16
	v_rcp_f32_e32 v20, v20
	v_add_f32_e32 v16, 1.0, v16
	v_rcp_f32_e32 v16, v16
	v_mul_f32_e32 v20, v33, v20
	v_mul_f32_e32 v28, v32, v20
	v_mov_b32_e32 v20, v29
	v_pk_mul_f32 v[20:21], v[20:21], v[134:135] op_sel_hi:[1,0]
	v_mul_f32_e32 v24, v35, v16
	v_mul_f32_e32 v16, 0xbfb8aa3b, v21
	v_exp_f32_e32 v29, v16
	v_mov_b32_e32 v16, v25
	v_pk_mul_f32 v[16:17], v[16:17], v[134:135] op_sel_hi:[1,0]
	v_mul_f32_e32 v32, v34, v24
	v_mul_f32_e32 v25, 0xbfb8aa3b, v17
	v_exp_f32_e32 v25, v25
	v_add_f32_e32 v24, 1.0, v29
	v_rcp_f32_e32 v29, v24
	v_add_f32_e32 v24, 1.0, v25
	v_rcp_f32_e32 v33, v24
	v_mov_b32_e32 v24, v30
	v_mov_b32_e32 v25, v22
	v_pk_mul_f32 v[24:25], v[24:25], v[134:135] op_sel_hi:[1,0]
	v_mul_f32_e32 v21, v21, v29
	v_mul_f32_e32 v22, 0xbfb8aa3b, v25
	v_exp_f32_e32 v22, v22
	v_mul_f32_e32 v29, v20, v21
	v_mov_b32_e32 v21, v18
	v_mul_f32_e32 v17, v17, v33
	v_add_f32_e32 v20, 1.0, v22
	v_rcp_f32_e32 v22, v20
	v_mov_b32_e32 v20, v26
	v_pk_mul_f32 v[20:21], v[20:21], v[134:135] op_sel_hi:[1,0]
	v_mul_f32_e32 v26, v16, v17
	v_mul_f32_e32 v18, 0xbfb8aa3b, v21
	v_exp_f32_e32 v18, v18
	v_mul_f32_e32 v16, v25, v22
	v_mul_f32_e32 v24, v24, v16
	v_mov_b32_e32 v22, v31
	v_add_f32_e32 v16, 1.0, v18
	v_rcp_f32_e32 v25, v16
	v_pk_mul_f32 v[16:17], v[22:23], v[134:135] op_sel_hi:[1,0]
	v_mul_f32_e32 v21, v21, v25
	v_mul_f32_e32 v18, 0xbfb8aa3b, v17
	v_exp_f32_e32 v22, v18
	v_mov_b32_e32 v18, v27
	v_pk_mul_f32 v[18:19], v[18:19], v[134:135] op_sel_hi:[1,0]
	v_mul_f32_e32 v20, v20, v21
	v_mul_f32_e32 v23, 0xbfb8aa3b, v19
	v_exp_f32_e32 v23, v23
	v_add_f32_e32 v22, 1.0, v22
	v_rcp_f32_e32 v22, v22
	v_add_f32_e32 v23, 1.0, v23
	v_rcp_f32_e32 v23, v23
	v_mul_f32_e32 v17, v17, v22
	v_mul_f32_e32 v17, v16, v17
	v_cvt_pk_bf16_f32 v17, v24, v17
	v_mul_f32_e32 v16, v19, v23
	v_mul_f32_e32 v19, v18, v16
	v_cvt_pk_bf16_f32 v19, v20, v19
	v_mad_i64_i32 v[20:21], s[22:23], v135, s36, v[112:113]
	v_lshl_add_u64 v[20:21], v[20:21], 0, s[20:21]
	v_lshl_add_u64 v[20:21], v[20:21], 0, v[128:129]
	v_lshl_add_u64 v[20:21], v[20:21], 0, v[114:115]
	v_cvt_pk_bf16_f32 v16, v28, v29
	v_cvt_pk_bf16_f32 v18, v32, v26
	global_store_dwordx4 v[20:21], v[16:19], off nt
	s_nop 1
	v_mov_b32_e32 v16, v12
	v_mov_b32_e32 v17, v4
	v_pk_mul_f32 v[16:17], v[16:17], v[130:131] op_sel_hi:[1,0]
	v_mov_b32_e32 v18, v8
	v_mul_f32_e32 v4, 0xbfb8aa3b, v17
	v_exp_f32_e32 v4, v4
	v_mov_b32_e32 v19, v0
	v_pk_mul_f32 v[18:19], v[18:19], v[130:131] op_sel_hi:[1,0]
	v_add_f32_e32 v4, 1.0, v4
	v_mul_f32_e32 v0, 0xbfb8aa3b, v19
	v_exp_f32_e32 v0, v0
	v_rcp_f32_e32 v4, v4
	v_add_f32_e32 v0, 1.0, v0
	v_rcp_f32_e32 v0, v0
	v_mul_f32_e32 v4, v17, v4
	v_mul_f32_e32 v12, v16, v4
	v_mov_b32_e32 v4, v13
	v_pk_mul_f32 v[4:5], v[4:5], v[130:131] op_sel_hi:[1,0]
	v_mul_f32_e32 v8, v19, v0
	v_mul_f32_e32 v0, 0xbfb8aa3b, v5
	v_exp_f32_e32 v13, v0
	v_mov_b32_e32 v0, v9
	v_pk_mul_f32 v[0:1], v[0:1], v[130:131] op_sel_hi:[1,0]
	v_mul_f32_e32 v16, v18, v8
	v_mul_f32_e32 v9, 0xbfb8aa3b, v1
	v_exp_f32_e32 v9, v9
	v_add_f32_e32 v8, 1.0, v13
	v_rcp_f32_e32 v13, v8
	v_add_f32_e32 v8, 1.0, v9
	v_rcp_f32_e32 v17, v8
	v_mov_b32_e32 v8, v14
	v_mov_b32_e32 v9, v6
	v_pk_mul_f32 v[8:9], v[8:9], v[130:131] op_sel_hi:[1,0]
	v_mul_f32_e32 v5, v5, v13
	v_mul_f32_e32 v6, 0xbfb8aa3b, v9
	v_exp_f32_e32 v6, v6
	v_mul_f32_e32 v13, v4, v5
	v_mov_b32_e32 v5, v2
	v_mul_f32_e32 v1, v1, v17
	v_add_f32_e32 v4, 1.0, v6
	v_rcp_f32_e32 v6, v4
	v_mov_b32_e32 v4, v10
	v_pk_mul_f32 v[4:5], v[4:5], v[130:131] op_sel_hi:[1,0]
	v_mul_f32_e32 v10, v0, v1
	v_mul_f32_e32 v2, 0xbfb8aa3b, v5
	v_exp_f32_e32 v2, v2
	v_mul_f32_e32 v0, v9, v6
	v_mul_f32_e32 v8, v8, v0
	v_mov_b32_e32 v6, v15
	v_add_f32_e32 v0, 1.0, v2
	v_rcp_f32_e32 v9, v0
	v_pk_mul_f32 v[0:1], v[6:7], v[130:131] op_sel_hi:[1,0]
	v_mul_f32_e32 v5, v5, v9
	v_mul_f32_e32 v2, 0xbfb8aa3b, v1
	v_exp_f32_e32 v6, v2
	v_mov_b32_e32 v2, v11
	v_pk_mul_f32 v[2:3], v[2:3], v[130:131] op_sel_hi:[1,0]
	v_mul_f32_e32 v4, v4, v5
	v_mul_f32_e32 v7, 0xbfb8aa3b, v3
	v_exp_f32_e32 v7, v7
	v_add_f32_e32 v6, 1.0, v6
	v_rcp_f32_e32 v6, v6
	v_add_f32_e32 v7, 1.0, v7
	v_rcp_f32_e32 v7, v7
	v_mul_f32_e32 v1, v1, v6
	v_mul_f32_e32 v1, v0, v1
	v_cvt_pk_bf16_f32 v1, v8, v1
	v_mul_f32_e32 v0, v3, v7
	v_mul_f32_e32 v3, v2, v0
	v_cvt_pk_bf16_f32 v3, v4, v3
	v_mad_i64_i32 v[4:5], s[22:23], v131, s36, v[112:113]
	v_lshl_add_u64 v[4:5], v[4:5], 0, s[20:21]
	v_lshl_add_u64 v[4:5], v[4:5], 0, v[128:129]
	v_lshl_add_u64 v[4:5], v[4:5], 0, v[114:115]
	v_cvt_pk_bf16_f32 v0, v12, v13
	v_cvt_pk_bf16_f32 v2, v16, v10
	global_store_dwordx4 v[4:5], v[0:3], off nt

.LBB0_1322:
	v_mov_b32_e32 v150, v124
	v_mov_b32_e32 v151, v116
	s_waitcnt vmcnt(0)
	v_pk_mul_f32 v[150:151], v[150:151], v[128:129] op_sel_hi:[1,0]
	v_mov_b32_e32 v152, v120
	v_mul_f32_e32 v116, 0xbfb8aa3b, v151
	v_exp_f32_e32 v116, v116
	v_mov_b32_e32 v153, v112
	v_pk_mul_f32 v[152:153], v[152:153], v[128:129] op_sel_hi:[1,0]
	s_lshl_b32 s40, s20, 7
	v_mul_f32_e32 v112, 0xbfb8aa3b, v153
	v_exp_f32_e32 v112, v112
	v_add_f32_e32 v116, 1.0, v116
	v_rcp_f32_e32 v116, v116
	s_ashr_i32 s41, s40, 31
	v_add_f32_e32 v112, 1.0, v112
	v_rcp_f32_e32 v112, v112
	v_mul_f32_e32 v116, v151, v116
	v_mul_f32_e32 v124, v150, v116
	v_mov_b32_e32 v116, v125
	v_pk_mul_f32 v[116:117], v[116:117], v[128:129] op_sel_hi:[1,0]
	v_mul_f32_e32 v120, v153, v112
	v_mul_f32_e32 v112, 0xbfb8aa3b, v117
	v_exp_f32_e32 v125, v112
	v_mov_b32_e32 v112, v121
	v_pk_mul_f32 v[112:113], v[112:113], v[128:129] op_sel_hi:[1,0]
	v_mul_f32_e32 v150, v152, v120
	v_mul_f32_e32 v121, 0xbfb8aa3b, v113
	v_exp_f32_e32 v121, v121
	v_add_f32_e32 v120, 1.0, v125
	v_rcp_f32_e32 v125, v120
	s_lshl_b64 s[40:41], s[40:41], 1
	v_add_f32_e32 v120, 1.0, v121
	v_rcp_f32_e32 v151, v120
	v_mov_b32_e32 v120, v126
	v_mov_b32_e32 v121, v118
	v_pk_mul_f32 v[120:121], v[120:121], v[128:129] op_sel_hi:[1,0]
	v_mul_f32_e32 v117, v117, v125
	v_mul_f32_e32 v118, 0xbfb8aa3b, v121
	v_exp_f32_e32 v118, v118
	v_mul_f32_e32 v125, v116, v117
	v_mov_b32_e32 v117, v114
	v_mul_f32_e32 v113, v113, v151
	v_add_f32_e32 v116, 1.0, v118
	v_rcp_f32_e32 v118, v116
	v_mov_b32_e32 v116, v122
	v_pk_mul_f32 v[116:117], v[116:117], v[128:129] op_sel_hi:[1,0]
	v_mul_f32_e32 v122, v112, v113
	v_mul_f32_e32 v114, 0xbfb8aa3b, v117
	v_exp_f32_e32 v114, v114
	v_mul_f32_e32 v112, v121, v118
	v_mul_f32_e32 v120, v120, v112
	v_mov_b32_e32 v118, v127
	v_add_f32_e32 v112, 1.0, v114
	v_rcp_f32_e32 v121, v112
	v_pk_mul_f32 v[112:113], v[118:119], v[128:129] op_sel_hi:[1,0]
	v_or_b32_e32 v145, 16, v148
	v_mul_f32_e32 v114, 0xbfb8aa3b, v113
	v_exp_f32_e32 v118, v114
	v_mov_b32_e32 v114, v123
	v_pk_mul_f32 v[114:115], v[114:115], v[128:129] op_sel_hi:[1,0]
	v_mul_f32_e32 v117, v117, v121
	v_mul_f32_e32 v119, 0xbfb8aa3b, v115
	v_exp_f32_e32 v119, v119
	v_add_f32_e32 v118, 1.0, v118
	v_rcp_f32_e32 v118, v118
	v_mul_f32_e32 v121, v116, v117
	v_add_f32_e32 v119, 1.0, v119
	v_rcp_f32_e32 v119, v119
	v_mul_f32_e32 v113, v113, v118
	v_mul_f32_e32 v112, v112, v113
	v_cvt_pk_bf16_f32 v117, v120, v112
	v_mul_f32_e32 v113, v115, v119
	v_mul_f32_e32 v113, v114, v113
	v_cvt_pk_bf16_f32 v119, v121, v113
	v_mov_b64_e32 v[112:113], s[66:67]
	v_mad_i64_i32 v[114:115], s[50:51], v148, s36, v[112:113]
	v_lshl_add_u64 v[114:115], v[114:115], 0, s[40:41]
	v_and_b32_e32 v128, 0xc0, v143
	v_lshl_add_u64 v[120:121], v[114:115], 0, v[128:129]
	v_and_b32_e32 v114, 48, v143
	v_mov_b32_e32 v115, v129
	v_lshl_add_u64 v[120:121], v[120:121], 0, v[114:115]
	v_or_b32_e32 v147, 32, v148
	v_or_b32_e32 v149, 48, v148
	v_add_u32_e32 v141, 0x80, v148
	v_add_u32_e32 v139, 0x90, v148
	v_add_u32_e32 v135, 0xa0, v148
	v_add_u32_e32 v131, 0xb0, v148
	v_cvt_pk_bf16_f32 v116, v124, v125
	v_cvt_pk_bf16_f32 v118, v150, v122
	global_store_dwordx4 v[120:121], v[116:119], off nt
	s_nop 1
	v_mov_b32_e32 v116, v108
	v_mov_b32_e32 v117, v100
	v_pk_mul_f32 v[116:117], v[116:117], v[146:147] op_sel_hi:[1,0]
	v_mov_b32_e32 v118, v104
	v_mul_f32_e32 v100, 0xbfb8aa3b, v117
	v_exp_f32_e32 v100, v100
	v_mov_b32_e32 v119, v96
	v_pk_mul_f32 v[118:119], v[118:119], v[146:147] op_sel_hi:[1,0]
	v_add_f32_e32 v100, 1.0, v100
	v_mul_f32_e32 v96, 0xbfb8aa3b, v119
	v_exp_f32_e32 v96, v96
	v_rcp_f32_e32 v100, v100
	v_add_f32_e32 v96, 1.0, v96
	v_rcp_f32_e32 v96, v96
	v_mul_f32_e32 v100, v117, v100
	v_mul_f32_e32 v108, v116, v100
	v_mov_b32_e32 v100, v109
	v_pk_mul_f32 v[100:101], v[100:101], v[146:147] op_sel_hi:[1,0]
	v_mul_f32_e32 v104, v119, v96
	v_mul_f32_e32 v96, 0xbfb8aa3b, v101
	v_exp_f32_e32 v109, v96
	v_mov_b32_e32 v96, v105
	v_pk_mul_f32 v[96:97], v[96:97], v[146:147] op_sel_hi:[1,0]
	v_mul_f32_e32 v116, v118, v104
	v_mul_f32_e32 v105, 0xbfb8aa3b, v97
	v_exp_f32_e32 v105, v105
	v_add_f32_e32 v104, 1.0, v109
	v_rcp_f32_e32 v109, v104
	v_add_f32_e32 v104, 1.0, v105
	v_rcp_f32_e32 v117, v104
	v_mov_b32_e32 v104, v110
	v_mov_b32_e32 v105, v102
	v_pk_mul_f32 v[104:105], v[104:105], v[146:147] op_sel_hi:[1,0]
	v_mul_f32_e32 v101, v101, v109
	v_mul_f32_e32 v102, 0xbfb8aa3b, v105
	v_exp_f32_e32 v102, v102
	v_mul_f32_e32 v109, v100, v101
	v_mov_b32_e32 v101, v98
	v_mul_f32_e32 v97, v97, v117
	v_add_f32_e32 v100, 1.0, v102
	v_rcp_f32_e32 v102, v100
	v_mov_b32_e32 v100, v106
	v_pk_mul_f32 v[100:101], v[100:101], v[146:147] op_sel_hi:[1,0]
	v_mul_f32_e32 v106, v96, v97
	v_mul_f32_e32 v98, 0xbfb8aa3b, v101
	v_exp_f32_e32 v98, v98
	v_mul_f32_e32 v96, v105, v102
	v_mul_f32_e32 v104, v104, v96
	v_mov_b32_e32 v102, v111
	v_add_f32_e32 v96, 1.0, v98
	v_rcp_f32_e32 v105, v96
	v_pk_mul_f32 v[96:97], v[102:103], v[146:147] op_sel_hi:[1,0]
	v_mul_f32_e32 v101, v101, v105
	v_mul_f32_e32 v98, 0xbfb8aa3b, v97
	v_exp_f32_e32 v102, v98
	v_mov_b32_e32 v98, v107
	v_pk_mul_f32 v[98:99], v[98:99], v[146:147] op_sel_hi:[1,0]
	v_mul_f32_e32 v100, v100, v101
	v_mul_f32_e32 v103, 0xbfb8aa3b, v99
	v_exp_f32_e32 v103, v103
	v_add_f32_e32 v102, 1.0, v102
	v_rcp_f32_e32 v102, v102
	v_add_f32_e32 v103, 1.0, v103
	v_rcp_f32_e32 v103, v103
	v_mul_f32_e32 v97, v97, v102
	v_mul_f32_e32 v97, v96, v97
	v_cvt_pk_bf16_f32 v97, v104, v97
	v_mul_f32_e32 v96, v99, v103
	v_mul_f32_e32 v99, v98, v96
	v_cvt_pk_bf16_f32 v99, v100, v99
	v_mad_i64_i32 v[100:101], s[50:51], v145, s36, v[112:113]
	v_lshl_add_u64 v[100:101], v[100:101], 0, s[40:41]
	v_lshl_add_u64 v[100:101], v[100:101], 0, v[128:129]
	v_lshl_add_u64 v[100:101], v[100:101], 0, v[114:115]
	v_cvt_pk_bf16_f32 v96, v108, v109
	v_cvt_pk_bf16_f32 v98, v116, v106
	global_store_dwordx4 v[100:101], v[96:99], off nt
	s_nop 1
	v_mov_b32_e32 v96, v92
	v_mov_b32_e32 v97, v84
	v_pk_mul_f32 v[96:97], v[96:97], v[144:145] op_sel_hi:[1,0]
	v_mov_b32_e32 v98, v88
	v_mul_f32_e32 v84, 0xbfb8aa3b, v97
	v_exp_f32_e32 v84, v84
	v_mov_b32_e32 v99, v80
	v_pk_mul_f32 v[98:99], v[98:99], v[144:145] op_sel_hi:[1,0]
	v_add_f32_e32 v84, 1.0, v84
	v_mul_f32_e32 v80, 0xbfb8aa3b, v99
	v_exp_f32_e32 v80, v80
	v_rcp_f32_e32 v84, v84
	v_add_f32_e32 v80, 1.0, v80
	v_rcp_f32_e32 v80, v80
	v_mul_f32_e32 v84, v97, v84
	v_mul_f32_e32 v92, v96, v84
	v_mov_b32_e32 v84, v93
	v_pk_mul_f32 v[84:85], v[84:85], v[144:145] op_sel_hi:[1,0]
	v_mul_f32_e32 v88, v99, v80
	v_mul_f32_e32 v80, 0xbfb8aa3b, v85
	v_exp_f32_e32 v93, v80
	v_mov_b32_e32 v80, v89
	v_pk_mul_f32 v[80:81], v[80:81], v[144:145] op_sel_hi:[1,0]
	v_mul_f32_e32 v96, v98, v88
	v_mul_f32_e32 v89, 0xbfb8aa3b, v81
	v_exp_f32_e32 v89, v89
	v_add_f32_e32 v88, 1.0, v93
	v_rcp_f32_e32 v93, v88
	v_add_f32_e32 v88, 1.0, v89
	v_rcp_f32_e32 v97, v88
	v_mov_b32_e32 v88, v94
	v_mov_b32_e32 v89, v86
	v_pk_mul_f32 v[88:89], v[88:89], v[144:145] op_sel_hi:[1,0]
	v_mul_f32_e32 v85, v85, v93
	v_mul_f32_e32 v86, 0xbfb8aa3b, v89
	v_exp_f32_e32 v86, v86
	v_mul_f32_e32 v93, v84, v85
	v_mov_b32_e32 v85, v82
	v_mul_f32_e32 v81, v81, v97
	v_add_f32_e32 v84, 1.0, v86
	v_rcp_f32_e32 v86, v84
	v_mov_b32_e32 v84, v90
	v_pk_mul_f32 v[84:85], v[84:85], v[144:145] op_sel_hi:[1,0]
	v_mul_f32_e32 v90, v80, v81
	v_mul_f32_e32 v82, 0xbfb8aa3b, v85
	v_exp_f32_e32 v82, v82
	v_mul_f32_e32 v80, v89, v86
	v_mul_f32_e32 v88, v88, v80
	v_mov_b32_e32 v86, v95
	v_add_f32_e32 v80, 1.0, v82
	v_rcp_f32_e32 v89, v80
	v_pk_mul_f32 v[80:81], v[86:87], v[144:145] op_sel_hi:[1,0]
	v_mul_f32_e32 v85, v85, v89
	v_mul_f32_e32 v82, 0xbfb8aa3b, v81
	v_exp_f32_e32 v86, v82
	v_mov_b32_e32 v82, v91
	v_pk_mul_f32 v[82:83], v[82:83], v[144:145] op_sel_hi:[1,0]
	v_mul_f32_e32 v84, v84, v85
	v_mul_f32_e32 v87, 0xbfb8aa3b, v83
	v_exp_f32_e32 v87, v87
	v_add_f32_e32 v86, 1.0, v86
	v_rcp_f32_e32 v86, v86
	v_add_f32_e32 v87, 1.0, v87
	v_rcp_f32_e32 v87, v87
	v_mul_f32_e32 v81, v81, v86
	v_mul_f32_e32 v81, v80, v81
	v_cvt_pk_bf16_f32 v81, v88, v81
	v_mul_f32_e32 v80, v83, v87
	v_mul_f32_e32 v83, v82, v80
	v_cvt_pk_bf16_f32 v83, v84, v83
	v_mad_i64_i32 v[84:85], s[50:51], v147, s36, v[112:113]
	v_lshl_add_u64 v[84:85], v[84:85], 0, s[40:41]
	v_lshl_add_u64 v[84:85], v[84:85], 0, v[128:129]
	v_lshl_add_u64 v[84:85], v[84:85], 0, v[114:115]
	v_cvt_pk_bf16_f32 v80, v92, v93
	v_cvt_pk_bf16_f32 v82, v96, v90
	global_store_dwordx4 v[84:85], v[80:83], off nt
	s_nop 1
	v_mov_b32_e32 v80, v76
	v_mov_b32_e32 v81, v68
	v_pk_mul_f32 v[80:81], v[80:81], v[142:143] op_sel_hi:[1,0]
	v_mov_b32_e32 v82, v72
	v_mul_f32_e32 v68, 0xbfb8aa3b, v81
	v_exp_f32_e32 v68, v68
	v_mov_b32_e32 v83, v64
	v_pk_mul_f32 v[82:83], v[82:83], v[142:143] op_sel_hi:[1,0]
	v_add_f32_e32 v68, 1.0, v68
	v_mul_f32_e32 v64, 0xbfb8aa3b, v83
	v_exp_f32_e32 v64, v64
	v_rcp_f32_e32 v68, v68
	v_add_f32_e32 v64, 1.0, v64
	v_rcp_f32_e32 v64, v64
	v_mul_f32_e32 v68, v81, v68
	v_mul_f32_e32 v76, v80, v68
	v_mov_b32_e32 v68, v77
	v_pk_mul_f32 v[68:69], v[68:69], v[142:143] op_sel_hi:[1,0]
	v_mul_f32_e32 v72, v83, v64
	v_mul_f32_e32 v64, 0xbfb8aa3b, v69
	v_exp_f32_e32 v77, v64
	v_mov_b32_e32 v64, v73
	v_pk_mul_f32 v[64:65], v[64:65], v[142:143] op_sel_hi:[1,0]
	v_mul_f32_e32 v80, v82, v72
	v_mul_f32_e32 v73, 0xbfb8aa3b, v65
	v_exp_f32_e32 v73, v73
	v_add_f32_e32 v72, 1.0, v77
	v_rcp_f32_e32 v77, v72
	v_add_f32_e32 v72, 1.0, v73
	v_rcp_f32_e32 v81, v72
	v_mov_b32_e32 v72, v78
	v_mov_b32_e32 v73, v70
	v_pk_mul_f32 v[72:73], v[72:73], v[142:143] op_sel_hi:[1,0]
	v_mul_f32_e32 v69, v69, v77
	v_mul_f32_e32 v70, 0xbfb8aa3b, v73
	v_exp_f32_e32 v70, v70
	v_mul_f32_e32 v77, v68, v69
	v_mov_b32_e32 v69, v66
	v_mul_f32_e32 v65, v65, v81
	v_add_f32_e32 v68, 1.0, v70
	v_rcp_f32_e32 v70, v68
	v_mov_b32_e32 v68, v74
	v_pk_mul_f32 v[68:69], v[68:69], v[142:143] op_sel_hi:[1,0]
	v_mul_f32_e32 v74, v64, v65
	v_mul_f32_e32 v66, 0xbfb8aa3b, v69
	v_exp_f32_e32 v66, v66
	v_mul_f32_e32 v64, v73, v70
	v_mul_f32_e32 v72, v72, v64
	v_mov_b32_e32 v70, v79
	v_add_f32_e32 v64, 1.0, v66
	v_rcp_f32_e32 v73, v64
	v_pk_mul_f32 v[64:65], v[70:71], v[142:143] op_sel_hi:[1,0]
	v_mul_f32_e32 v69, v69, v73
	v_mul_f32_e32 v66, 0xbfb8aa3b, v65
	v_exp_f32_e32 v70, v66
	v_mov_b32_e32 v66, v75
	v_pk_mul_f32 v[66:67], v[66:67], v[142:143] op_sel_hi:[1,0]
	v_mul_f32_e32 v68, v68, v69
	v_mul_f32_e32 v71, 0xbfb8aa3b, v67
	v_exp_f32_e32 v71, v71
	v_add_f32_e32 v70, 1.0, v70
	v_rcp_f32_e32 v70, v70
	v_add_f32_e32 v71, 1.0, v71
	v_rcp_f32_e32 v71, v71
	v_mul_f32_e32 v65, v65, v70
	v_mul_f32_e32 v65, v64, v65
	v_cvt_pk_bf16_f32 v65, v72, v65
	v_mul_f32_e32 v64, v67, v71
	v_mul_f32_e32 v67, v66, v64
	v_cvt_pk_bf16_f32 v67, v68, v67
	v_mad_i64_i32 v[68:69], s[50:51], v149, s36, v[112:113]
	v_lshl_add_u64 v[68:69], v[68:69], 0, s[40:41]
	v_lshl_add_u64 v[68:69], v[68:69], 0, v[128:129]
	v_lshl_add_u64 v[68:69], v[68:69], 0, v[114:115]
	v_cvt_pk_bf16_f32 v64, v76, v77
	v_cvt_pk_bf16_f32 v66, v80, v74
	global_store_dwordx4 v[68:69], v[64:67], off nt
	s_nop 1
	v_mov_b32_e32 v64, v60
	v_mov_b32_e32 v65, v52
	v_pk_mul_f32 v[64:65], v[64:65], v[140:141] op_sel_hi:[1,0]
	v_mov_b32_e32 v66, v56
	v_mul_f32_e32 v52, 0xbfb8aa3b, v65
	v_exp_f32_e32 v52, v52
	v_mov_b32_e32 v67, v48
	v_pk_mul_f32 v[66:67], v[66:67], v[140:141] op_sel_hi:[1,0]
	v_add_f32_e32 v52, 1.0, v52
	v_mul_f32_e32 v48, 0xbfb8aa3b, v67
	v_exp_f32_e32 v48, v48
	v_rcp_f32_e32 v52, v52
	v_add_f32_e32 v48, 1.0, v48
	v_rcp_f32_e32 v48, v48
	v_mul_f32_e32 v52, v65, v52
	v_mul_f32_e32 v60, v64, v52
	v_mov_b32_e32 v52, v61
	v_pk_mul_f32 v[52:53], v[52:53], v[140:141] op_sel_hi:[1,0]
	v_mul_f32_e32 v56, v67, v48
	v_mul_f32_e32 v48, 0xbfb8aa3b, v53
	v_exp_f32_e32 v61, v48
	v_mov_b32_e32 v48, v57
	v_pk_mul_f32 v[48:49], v[48:49], v[140:141] op_sel_hi:[1,0]
	v_mul_f32_e32 v64, v66, v56
	v_mul_f32_e32 v57, 0xbfb8aa3b, v49
	v_exp_f32_e32 v57, v57
	v_add_f32_e32 v56, 1.0, v61
	v_rcp_f32_e32 v61, v56
	v_add_f32_e32 v56, 1.0, v57
	v_rcp_f32_e32 v65, v56
	v_mov_b32_e32 v56, v62
	v_mov_b32_e32 v57, v54
	v_pk_mul_f32 v[56:57], v[56:57], v[140:141] op_sel_hi:[1,0]
	v_mul_f32_e32 v53, v53, v61
	v_mul_f32_e32 v54, 0xbfb8aa3b, v57
	v_exp_f32_e32 v54, v54
	v_mul_f32_e32 v61, v52, v53
	v_mov_b32_e32 v53, v50
	v_mul_f32_e32 v49, v49, v65
	v_add_f32_e32 v52, 1.0, v54
	v_rcp_f32_e32 v54, v52
	v_mov_b32_e32 v52, v58
	v_pk_mul_f32 v[52:53], v[52:53], v[140:141] op_sel_hi:[1,0]
	v_mul_f32_e32 v58, v48, v49
	v_mul_f32_e32 v50, 0xbfb8aa3b, v53
	v_exp_f32_e32 v50, v50
	v_mul_f32_e32 v48, v57, v54
	v_mul_f32_e32 v56, v56, v48
	v_mov_b32_e32 v54, v63
	v_add_f32_e32 v48, 1.0, v50
	v_rcp_f32_e32 v57, v48
	v_pk_mul_f32 v[48:49], v[54:55], v[140:141] op_sel_hi:[1,0]
	v_mul_f32_e32 v53, v53, v57
	v_mul_f32_e32 v50, 0xbfb8aa3b, v49
	v_exp_f32_e32 v54, v50
	v_mov_b32_e32 v50, v59
	v_pk_mul_f32 v[50:51], v[50:51], v[140:141] op_sel_hi:[1,0]
	v_mul_f32_e32 v52, v52, v53
	v_mul_f32_e32 v55, 0xbfb8aa3b, v51
	v_exp_f32_e32 v55, v55
	v_add_f32_e32 v54, 1.0, v54
	v_rcp_f32_e32 v54, v54
	v_add_f32_e32 v55, 1.0, v55
	v_rcp_f32_e32 v55, v55
	v_mul_f32_e32 v49, v49, v54
	v_mul_f32_e32 v49, v48, v49
	v_cvt_pk_bf16_f32 v49, v56, v49
	v_mul_f32_e32 v48, v51, v55
	v_mul_f32_e32 v51, v50, v48
	v_cvt_pk_bf16_f32 v51, v52, v51
	v_mad_i64_i32 v[52:53], s[50:51], v141, s36, v[112:113]
	v_lshl_add_u64 v[52:53], v[52:53], 0, s[40:41]
	v_lshl_add_u64 v[52:53], v[52:53], 0, v[128:129]
	v_lshl_add_u64 v[52:53], v[52:53], 0, v[114:115]
	v_cvt_pk_bf16_f32 v48, v60, v61
	v_cvt_pk_bf16_f32 v50, v64, v58
	global_store_dwordx4 v[52:53], v[48:51], off nt
	s_nop 1
	v_mov_b32_e32 v48, v44
	v_mov_b32_e32 v49, v36
	v_pk_mul_f32 v[48:49], v[48:49], v[138:139] op_sel_hi:[1,0]
	v_mov_b32_e32 v50, v40
	v_mul_f32_e32 v36, 0xbfb8aa3b, v49
	v_exp_f32_e32 v36, v36
	v_mov_b32_e32 v51, v32
	v_pk_mul_f32 v[50:51], v[50:51], v[138:139] op_sel_hi:[1,0]
	v_add_f32_e32 v36, 1.0, v36
	v_mul_f32_e32 v32, 0xbfb8aa3b, v51
	v_exp_f32_e32 v32, v32
	v_rcp_f32_e32 v36, v36
	v_add_f32_e32 v32, 1.0, v32
	v_rcp_f32_e32 v32, v32
	v_mul_f32_e32 v36, v49, v36
	v_mul_f32_e32 v44, v48, v36
	v_mov_b32_e32 v36, v45
	v_pk_mul_f32 v[36:37], v[36:37], v[138:139] op_sel_hi:[1,0]
	v_mul_f32_e32 v40, v51, v32
	v_mul_f32_e32 v32, 0xbfb8aa3b, v37
	v_exp_f32_e32 v45, v32
	v_mov_b32_e32 v32, v41
	v_pk_mul_f32 v[32:33], v[32:33], v[138:139] op_sel_hi:[1,0]
	v_mul_f32_e32 v48, v50, v40
	v_mul_f32_e32 v41, 0xbfb8aa3b, v33
	v_exp_f32_e32 v41, v41
	v_add_f32_e32 v40, 1.0, v45
	v_rcp_f32_e32 v45, v40
	v_add_f32_e32 v40, 1.0, v41
	v_rcp_f32_e32 v49, v40
	v_mov_b32_e32 v40, v46
	v_mov_b32_e32 v41, v38
	v_pk_mul_f32 v[40:41], v[40:41], v[138:139] op_sel_hi:[1,0]
	v_mul_f32_e32 v37, v37, v45
	v_mul_f32_e32 v38, 0xbfb8aa3b, v41
	v_exp_f32_e32 v38, v38
	v_mul_f32_e32 v45, v36, v37
	v_mov_b32_e32 v37, v34
	v_mul_f32_e32 v33, v33, v49
	v_add_f32_e32 v36, 1.0, v38
	v_rcp_f32_e32 v38, v36
	v_mov_b32_e32 v36, v42
	v_pk_mul_f32 v[36:37], v[36:37], v[138:139] op_sel_hi:[1,0]
	v_mul_f32_e32 v42, v32, v33
	v_mul_f32_e32 v34, 0xbfb8aa3b, v37
	v_exp_f32_e32 v34, v34
	v_mul_f32_e32 v32, v41, v38
	v_mul_f32_e32 v40, v40, v32
	v_mov_b32_e32 v38, v47
	v_add_f32_e32 v32, 1.0, v34
	v_rcp_f32_e32 v41, v32
	v_pk_mul_f32 v[32:33], v[38:39], v[138:139] op_sel_hi:[1,0]
	v_mul_f32_e32 v37, v37, v41
	v_mul_f32_e32 v34, 0xbfb8aa3b, v33
	v_exp_f32_e32 v38, v34
	v_mov_b32_e32 v34, v43
	v_pk_mul_f32 v[34:35], v[34:35], v[138:139] op_sel_hi:[1,0]
	v_mul_f32_e32 v36, v36, v37
	v_mul_f32_e32 v39, 0xbfb8aa3b, v35
	v_exp_f32_e32 v39, v39
	v_add_f32_e32 v38, 1.0, v38
	v_rcp_f32_e32 v38, v38
	v_add_f32_e32 v39, 1.0, v39
	v_rcp_f32_e32 v39, v39
	v_mul_f32_e32 v33, v33, v38
	v_mul_f32_e32 v33, v32, v33
	v_cvt_pk_bf16_f32 v33, v40, v33
	v_mul_f32_e32 v32, v35, v39
	v_mul_f32_e32 v35, v34, v32
	v_cvt_pk_bf16_f32 v35, v36, v35
	v_mad_i64_i32 v[36:37], s[50:51], v139, s36, v[112:113]
	v_lshl_add_u64 v[36:37], v[36:37], 0, s[40:41]
	v_lshl_add_u64 v[36:37], v[36:37], 0, v[128:129]
	v_lshl_add_u64 v[36:37], v[36:37], 0, v[114:115]
	v_cvt_pk_bf16_f32 v32, v44, v45
	v_cvt_pk_bf16_f32 v34, v48, v42
	global_store_dwordx4 v[36:37], v[32:35], off nt
	s_nop 1
	v_mov_b32_e32 v32, v28
	v_mov_b32_e32 v33, v20
	v_pk_mul_f32 v[32:33], v[32:33], v[134:135] op_sel_hi:[1,0]
	v_mov_b32_e32 v34, v24
	v_mul_f32_e32 v20, 0xbfb8aa3b, v33
	v_exp_f32_e32 v20, v20
	v_mov_b32_e32 v35, v16
	v_pk_mul_f32 v[34:35], v[34:35], v[134:135] op_sel_hi:[1,0]
	v_add_f32_e32 v20, 1.0, v20
	v_mul_f32_e32 v16, 0xbfb8aa3b, v35
	v_exp_f32_e32 v16, v16
	v_rcp_f32_e32 v20, v20
	v_add_f32_e32 v16, 1.0, v16
	v_rcp_f32_e32 v16, v16
	v_mul_f32_e32 v20, v33, v20
	v_mul_f32_e32 v28, v32, v20
	v_mov_b32_e32 v20, v29
	v_pk_mul_f32 v[20:21], v[20:21], v[134:135] op_sel_hi:[1,0]
	v_mul_f32_e32 v24, v35, v16
	v_mul_f32_e32 v16, 0xbfb8aa3b, v21
	v_exp_f32_e32 v29, v16
	v_mov_b32_e32 v16, v25
	v_pk_mul_f32 v[16:17], v[16:17], v[134:135] op_sel_hi:[1,0]
	v_mul_f32_e32 v32, v34, v24
	v_mul_f32_e32 v25, 0xbfb8aa3b, v17
	v_exp_f32_e32 v25, v25
	v_add_f32_e32 v24, 1.0, v29
	v_rcp_f32_e32 v29, v24
	v_add_f32_e32 v24, 1.0, v25
	v_rcp_f32_e32 v33, v24
	v_mov_b32_e32 v24, v30
	v_mov_b32_e32 v25, v22
	v_pk_mul_f32 v[24:25], v[24:25], v[134:135] op_sel_hi:[1,0]
	v_mul_f32_e32 v21, v21, v29
	v_mul_f32_e32 v22, 0xbfb8aa3b, v25
	v_exp_f32_e32 v22, v22
	v_mul_f32_e32 v29, v20, v21
	v_mov_b32_e32 v21, v18
	v_mul_f32_e32 v17, v17, v33
	v_add_f32_e32 v20, 1.0, v22
	v_rcp_f32_e32 v22, v20
	v_mov_b32_e32 v20, v26
	v_pk_mul_f32 v[20:21], v[20:21], v[134:135] op_sel_hi:[1,0]
	v_mul_f32_e32 v26, v16, v17
	v_mul_f32_e32 v18, 0xbfb8aa3b, v21
	v_exp_f32_e32 v18, v18
	v_mul_f32_e32 v16, v25, v22
	v_mul_f32_e32 v24, v24, v16
	v_mov_b32_e32 v22, v31
	v_add_f32_e32 v16, 1.0, v18
	v_rcp_f32_e32 v25, v16
	v_pk_mul_f32 v[16:17], v[22:23], v[134:135] op_sel_hi:[1,0]
	v_mul_f32_e32 v21, v21, v25
	v_mul_f32_e32 v18, 0xbfb8aa3b, v17
	v_exp_f32_e32 v22, v18
	v_mov_b32_e32 v18, v27
	v_pk_mul_f32 v[18:19], v[18:19], v[134:135] op_sel_hi:[1,0]
	v_mul_f32_e32 v20, v20, v21
	v_mul_f32_e32 v23, 0xbfb8aa3b, v19
	v_exp_f32_e32 v23, v23
	v_add_f32_e32 v22, 1.0, v22
	v_rcp_f32_e32 v22, v22
	v_add_f32_e32 v23, 1.0, v23
	v_rcp_f32_e32 v23, v23
	v_mul_f32_e32 v17, v17, v22
	v_mul_f32_e32 v17, v16, v17
	v_cvt_pk_bf16_f32 v17, v24, v17
	v_mul_f32_e32 v16, v19, v23
	v_mul_f32_e32 v19, v18, v16
	v_cvt_pk_bf16_f32 v19, v20, v19
	v_mad_i64_i32 v[20:21], s[50:51], v135, s36, v[112:113]
	v_lshl_add_u64 v[20:21], v[20:21], 0, s[40:41]
	v_lshl_add_u64 v[20:21], v[20:21], 0, v[128:129]
	v_lshl_add_u64 v[20:21], v[20:21], 0, v[114:115]
	v_cvt_pk_bf16_f32 v16, v28, v29
	v_cvt_pk_bf16_f32 v18, v32, v26
	global_store_dwordx4 v[20:21], v[16:19], off nt
	s_nop 1
	v_mov_b32_e32 v16, v12
	v_mov_b32_e32 v17, v4
	v_pk_mul_f32 v[16:17], v[16:17], v[130:131] op_sel_hi:[1,0]
	v_mov_b32_e32 v18, v8
	v_mul_f32_e32 v4, 0xbfb8aa3b, v17
	v_exp_f32_e32 v4, v4
	v_mov_b32_e32 v19, v0
	v_pk_mul_f32 v[18:19], v[18:19], v[130:131] op_sel_hi:[1,0]
	v_add_f32_e32 v4, 1.0, v4
	v_mul_f32_e32 v0, 0xbfb8aa3b, v19
	v_exp_f32_e32 v0, v0
	v_rcp_f32_e32 v4, v4
	v_add_f32_e32 v0, 1.0, v0
	v_rcp_f32_e32 v0, v0
	v_mul_f32_e32 v4, v17, v4
	v_mul_f32_e32 v12, v16, v4
	v_mov_b32_e32 v4, v13
	v_pk_mul_f32 v[4:5], v[4:5], v[130:131] op_sel_hi:[1,0]
	v_mul_f32_e32 v8, v19, v0
	v_mul_f32_e32 v0, 0xbfb8aa3b, v5
	v_exp_f32_e32 v13, v0
	v_mov_b32_e32 v0, v9
	v_pk_mul_f32 v[0:1], v[0:1], v[130:131] op_sel_hi:[1,0]
	v_mul_f32_e32 v16, v18, v8
	v_mul_f32_e32 v9, 0xbfb8aa3b, v1
	v_exp_f32_e32 v9, v9
	v_add_f32_e32 v8, 1.0, v13
	v_rcp_f32_e32 v13, v8
	v_add_f32_e32 v8, 1.0, v9
	v_rcp_f32_e32 v17, v8
	v_mov_b32_e32 v8, v14
	v_mov_b32_e32 v9, v6
	v_pk_mul_f32 v[8:9], v[8:9], v[130:131] op_sel_hi:[1,0]
	v_mul_f32_e32 v5, v5, v13
	v_mul_f32_e32 v6, 0xbfb8aa3b, v9
	v_exp_f32_e32 v6, v6
	v_mul_f32_e32 v13, v4, v5
	v_mov_b32_e32 v5, v2
	v_mul_f32_e32 v1, v1, v17
	v_add_f32_e32 v4, 1.0, v6
	v_rcp_f32_e32 v6, v4
	v_mov_b32_e32 v4, v10
	v_pk_mul_f32 v[4:5], v[4:5], v[130:131] op_sel_hi:[1,0]
	v_mul_f32_e32 v10, v0, v1
	v_mul_f32_e32 v2, 0xbfb8aa3b, v5
	v_exp_f32_e32 v2, v2
	v_mul_f32_e32 v0, v9, v6
	v_mul_f32_e32 v8, v8, v0
	v_mov_b32_e32 v6, v15
	v_add_f32_e32 v0, 1.0, v2
	v_rcp_f32_e32 v9, v0
	v_pk_mul_f32 v[0:1], v[6:7], v[130:131] op_sel_hi:[1,0]
	v_mul_f32_e32 v5, v5, v9
	v_mul_f32_e32 v2, 0xbfb8aa3b, v1
	v_exp_f32_e32 v6, v2
	v_mov_b32_e32 v2, v11
	v_pk_mul_f32 v[2:3], v[2:3], v[130:131] op_sel_hi:[1,0]
	v_mul_f32_e32 v4, v4, v5
	v_mul_f32_e32 v7, 0xbfb8aa3b, v3
	v_exp_f32_e32 v7, v7
	v_add_f32_e32 v6, 1.0, v6
	v_rcp_f32_e32 v6, v6
	v_add_f32_e32 v7, 1.0, v7
	v_rcp_f32_e32 v7, v7
	v_mul_f32_e32 v1, v1, v6
	v_mul_f32_e32 v1, v0, v1
	v_cvt_pk_bf16_f32 v1, v8, v1
	v_mul_f32_e32 v0, v3, v7
	v_mul_f32_e32 v3, v2, v0
	v_cvt_pk_bf16_f32 v3, v4, v3
	v_mad_i64_i32 v[4:5], s[50:51], v131, s36, v[112:113]
	v_lshl_add_u64 v[4:5], v[4:5], 0, s[40:41]
	v_lshl_add_u64 v[4:5], v[4:5], 0, v[128:129]
	v_lshl_add_u64 v[4:5], v[4:5], 0, v[114:115]
	v_cvt_pk_bf16_f32 v0, v12, v13
	v_cvt_pk_bf16_f32 v2, v16, v10
	global_store_dwordx4 v[4:5], v[0:3], off nt
	s_mov_b64 s[40:41], 0
